# v42 + in-proj A: side-job x row moved to v198-213, last two row groups' 4 stores parked in v0-15 and trickled into the next unit's K-loop
# speedup vs baseline: 1.0043x; 1.0043x over previous
; #define PG8_LAS __attribute__((address_space(3)))
;     __device__ __forceinline__ void stage_consts(PG8_LAS float* gl, int tid) const { if (tid < 2 * NGQ) gl[tid] = (tid < NGQ) ? qg[tid] * qscale : kg[tid - NGQ]; }
; #define PG8_STAGE(bufoff, gbase, voff) do { _Pragma("unroll") for (int _i = 0; _i < 2; ++_i) \
;         __builtin_amdgcn_global_load_lds((const unsigned*)((const char*)(gbase) + (voff)[_i]), (PG8_LAS unsigned*)(lds + (bufoff) + ldsw + _i * 8192), 16, 0, 0); } while (0)
; #define PG8_ZERO4(x) do { unsigned long long z0_, z1_; asm volatile("v_mov_b64 %0, 0\n\tv_mov_b64 %1, 0" : "=v"(z0_), "=v"(z1_)); typedef unsigned long long u64x2_ __attribute__((ext_vector_type(2))); (x) = __builtin_bit_cast(f32x4, (u64x2_){z0_, z1_}); } while (0)
;     ...
;     Unit cur, nxt; int ui = 0; int prev_pm = -1;
;     if (!S.next(0, cur)) return;
;     f32x4 acc[2][2][4][2];
; #pragma unroll
;     for (int a = 0; a < 2; ++a)
; #pragma unroll
;         for (int b = 0; b < 2; ++b)
; #pragma unroll
;             for (int m = 0; m < 4; ++m)
; #pragma unroll
;                 for (int n = 0; n < 2; ++n) PG8_ZERO4(acc[a][b][m][n]);
;     bf16x8 At[4][2], B0[2][2], B1[2][2];
;     const char* cA = (const char*)g.A + (size_t)cur.pm * tstep; const char* cB = (const char*)g.Bt + (size_t)cur.pn * tstep;
;     PG8_STAGE(PG8_SB(0, 0), cB, voffB); PG8_STAGE(PG8_SB(0, 1), cB + hstepB, voffB); PG8_STAGE(PG8_SA(0, 0), cA, voffA); PG8_STAGE(PG8_SA(0, 1), cA + hstep, voffA);
;     E.stage_consts((PG8_LAS float*)(lds + 131072) + 1024, tid);
.LBB0_190:
	s_lshl_b32 s62, s85, 1
	s_or_b32 s2, s62, 1
	s_cmp_le_i32 s66, s2
	s_cselect_b64 s[12:13], -1, 0
	s_cmp_lt_i32 s2, s67
	s_cselect_b64 s[14:15], -1, 0
	s_lshl_b32 s88, s85, 23
	s_and_b64 s[12:13], s[12:13], s[14:15]
	s_lshl_b64 s[14:15], s[88:89], 1
	s_add_u32 s16, s63, s14
	s_addc_u32 s17, s64, s15
	s_cmp_eq_u32 s85, 3
	s_cselect_b64 s[22:23], -1, 0
	s_cmp_lg_u32 s85, 3
	s_cselect_b64 s[14:15], -1, 0
	v_writelane_b32 v252, s14, 43
	s_add_i32 s2, s62, 2
	s_nop 0
	v_writelane_b32 v252, s15, 44
	s_lshl_b32 s14, s85, 6
	s_mov_b32 s15, s89
	v_writelane_b32 v252, s14, 45
	s_cmp_le_i32 s66, s2
	s_nop 0
	v_writelane_b32 v252, s15, 46
	s_cselect_b64 s[14:15], -1, 0
	s_cmp_lt_i32 s2, s67
	s_cselect_b64 s[18:19], -1, 0
	s_and_b64 s[18:19], s[14:15], s[18:19]
	s_and_b64 vcc, exec, s[12:13]
	s_cbranch_vccz .LBB0_302
	s_mov_b32 s101, 0
	v_readlane_b32 s12, v253, 57
	s_waitcnt vmcnt(0)
	v_mbcnt_lo_u32_b32 v8, -1, 0
	v_mbcnt_hi_u32_b32 v8, -1, v8
	v_readlane_b32 s13, v253, 58
	v_add_u32_e32 v0, s65, v8
	s_andn2_b64 vcc, exec, s[12:13]
	v_readfirstlane_b32 s2, v0
	s_cbranch_vccnz .LBB0_254
	v_lshlrev_b32_e32 v1, 4, v0
	v_add_u32_e32 v2, 0x2000, v1
	v_ashrrev_i32_e32 v3, 31, v2
	v_lshrrev_b32_e32 v3, 22, v3
	v_add_u32_e32 v3, v2, v3
	v_ashrrev_i32_e32 v9, 10, v3
	v_mul_i32_i24_e32 v3, 0x400, v9
	v_sub_u32_e32 v2, v2, v3
	v_lshrrev_b32_e32 v3, 4, v2
	v_bitop3_b32 v2, v3, v2, 32 bitop3:0x6c
	v_ashrrev_i32_e32 v3, 31, v2
	v_lshrrev_b32_e32 v3, 26, v3
	v_add_u32_e32 v3, v2, v3
	v_lshlrev_b32_e32 v5, 3, v9
	v_ashrrev_i32_e32 v10, 6, v3
	v_and_b32_e32 v5, -16, v5
	v_add_u32_e32 v5, v10, v5
	v_lshrrev_b32_e32 v6, 2, v5
	v_lshlrev_b32_e32 v7, 1, v5
	v_and_b32_e32 v3, 0xc0, v3
	v_and_b32_e32 v4, 3, v10
	v_and_b32_e32 v6, 4, v6
	v_and_b32_e32 v7, 0x1fffd8, v7
	v_sub_u32_e32 v2, v2, v3
	v_or3_b32 v4, v4, v6, v7
	v_lshlrev_b32_e32 v6, 5, v9
	v_ashrrev_i16_sdwa v2, v191, sext(v2) dst_sel:DWORD dst_unused:UNUSED_PAD src0_sel:DWORD src1_sel:BYTE_0
	v_and_b32_e32 v6, 32, v6
	v_bfe_i32 v11, v2, 0, 16
	v_add_lshl_u32 v2, v6, v11, 1
	v_lshl_add_u32 v166, v4, 11, v2
	v_lshl_add_u32 v168, v5, 11, v2
	v_bfe_i32 v2, v0, 27, 1
	v_lshrrev_b32_e32 v2, 22, v2
	v_add_u32_e32 v2, v1, v2
	v_and_b32_e32 v2, 0xfffffc00, v2
	v_sub_u32_e32 v1, v1, v2
	v_lshrrev_b32_e32 v2, 4, v1
	v_bitop3_b32 v2, v2, v1, 32 bitop3:0x6c
	v_ashrrev_i32_e32 v1, 31, v2
	v_lshrrev_b32_e32 v1, 26, v1
	v_add_u32_e32 v3, v2, v1
	v_ashrrev_i32_e32 v1, 31, v0
	v_lshrrev_b32_e32 v5, 26, v1
	v_add_u32_e32 v5, v0, v5
	v_ashrrev_i32_e32 v13, 6, v5
	v_lshlrev_b32_e32 v5, 3, v13
	v_ashrrev_i32_e32 v12, 6, v3
	v_and_b32_e32 v5, -16, v5
	v_add_u32_e32 v5, v12, v5
	v_lshrrev_b32_e32 v6, 2, v5
	v_lshlrev_b32_e32 v7, 1, v5
	v_and_b32_e32 v3, 0xc0, v3
	v_and_b32_e32 v4, 3, v12
	v_and_b32_e32 v6, 4, v6
	v_and_b32_e32 v7, 0x1fffd8, v7
	v_sub_u32_e32 v2, v2, v3
	s_ashr_i32 s14, s2, 6
	v_or3_b32 v4, v4, v6, v7
	v_lshlrev_b32_e32 v6, 5, v13
	v_ashrrev_i16_sdwa v2, v191, sext(v2) dst_sel:DWORD dst_unused:UNUSED_PAD src0_sel:DWORD src1_sel:BYTE_0
	s_lshl_b32 s15, s14, 10
	v_and_b32_e32 v6, 32, v6
	v_bfe_i32 v14, v2, 0, 16
	v_add_lshl_u32 v2, v6, v14, 1
	s_add_i32 s63, s15, 0
	v_readlane_b32 s12, v252, 13
	v_lshl_add_u32 v170, v4, 11, v2
	s_add_i32 m0, s63, 0x10000
	v_readlane_b32 s13, v252, 14
	v_mov_b64 v[132:133], 0
	v_mov_b64 v[134:135], 0
	v_mov_b64 v[128:129], 0
	v_mov_b64 v[130:131], 0
	v_mov_b64 v[116:117], 0
	v_mov_b64 v[118:119], 0
	v_mov_b64 v[112:113], 0
	v_mov_b64 v[114:115], 0
	v_mov_b64 v[100:101], 0
	v_mov_b64 v[102:103], 0
	v_mov_b64 v[96:97], 0
	v_mov_b64 v[98:99], 0
	v_mov_b64 v[84:85], 0
	v_mov_b64 v[86:87], 0
	v_mov_b64 v[80:81], 0
	v_mov_b64 v[82:83], 0
	v_mov_b64 v[140:141], 0
	v_mov_b64 v[142:143], 0
	v_mov_b64 v[136:137], 0
	v_mov_b64 v[138:139], 0
	v_mov_b64 v[124:125], 0
	v_mov_b64 v[126:127], 0
	v_mov_b64 v[120:121], 0
	v_mov_b64 v[122:123], 0
	v_mov_b64 v[108:109], 0
	v_mov_b64 v[110:111], 0
	v_mov_b64 v[104:105], 0
	v_mov_b64 v[106:107], 0
	v_mov_b64 v[92:93], 0
	v_mov_b64 v[94:95], 0
	v_mov_b64 v[88:89], 0
	v_mov_b64 v[90:91], 0
	v_mov_b64 v[68:69], 0
	v_mov_b64 v[70:71], 0
	v_mov_b64 v[64:65], 0
	v_mov_b64 v[66:67], 0
	v_mov_b64 v[52:53], 0
	v_mov_b64 v[54:55], 0
	v_mov_b64 v[48:49], 0
	v_mov_b64 v[50:51], 0
	v_mov_b64 v[36:37], 0
	v_mov_b64 v[38:39], 0
	v_mov_b64 v[32:33], 0
	v_mov_b64 v[34:35], 0
	v_mov_b64 v[20:21], 0
	v_mov_b64 v[22:23], 0
	v_mov_b64 v[16:17], 0
	v_mov_b64 v[18:19], 0
	v_mov_b64 v[76:77], 0
	v_mov_b64 v[78:79], 0
	v_mov_b64 v[72:73], 0
	v_mov_b64 v[74:75], 0
	v_mov_b64 v[60:61], 0
	v_mov_b64 v[62:63], 0
	v_mov_b64 v[56:57], 0
	v_mov_b64 v[58:59], 0
	v_mov_b64 v[44:45], 0
	v_mov_b64 v[46:47], 0
	v_mov_b64 v[40:41], 0
	v_mov_b64 v[42:43], 0
	v_mov_b64 v[24:25], 0
	v_mov_b64 v[26:27], 0
	v_mov_b64 v[28:29], 0
	v_mov_b64 v[30:31], 0
	s_nop 4
	global_load_lds_dwordx4 v170, s[12:13]
	s_add_i32 m0, s63, 0x12000
	v_lshl_add_u32 v172, v5, 11, v2
	global_load_lds_dwordx4 v166, s[12:13]
	v_readlane_b32 s12, v252, 11
	s_add_i32 m0, s63, 0x14000
	v_readlane_b32 s13, v252, 12
	s_nop 4
	global_load_lds_dwordx4 v170, s[12:13]
	s_add_i32 m0, s63, 0x16000
	s_nop 0
	global_load_lds_dwordx4 v166, s[12:13]
	v_readlane_b32 s12, v252, 9
	v_readlane_b32 s13, v252, 10
	s_add_u32 s38, s16, s12
	s_addc_u32 s39, s17, s13
	s_add_i32 s64, s63, 0x2000
	s_mov_b32 m0, s63
	s_add_u32 s12, s38, 0x40000
	global_load_lds_dwordx4 v172, s[38:39]
	s_mov_b32 m0, s64
	s_addc_u32 s13, s39, 0
	s_add_i32 s65, s63, 0x4000
	global_load_lds_dwordx4 v168, s[38:39]
	s_mov_b32 m0, s65
	s_add_i32 s66, s63, 0x6000
	global_load_lds_dwordx4 v172, s[12:13]
	s_mov_b32 m0, s66
	s_nop 0
	global_load_lds_dwordx4 v168, s[12:13]
	s_movk_i32 s12, 0x180
	v_cmp_gt_i32_e32 vcc, s12, v0
	s_and_saveexec_b64 s[20:21], vcc
	s_cbranch_execz .LBB0_198
	s_movk_i32 s12, 0xbf
	v_cmp_lt_i32_e32 vcc, s12, v0
	s_and_saveexec_b64 s[12:13], vcc
	s_xor_b64 s[24:25], exec, s[12:13]
	s_cbranch_execz .LBB0_195
	v_mov_b32_e32 v1, v161
	v_lshl_add_u64 v[2:3], v[0:1], 2, s[54:55]
	global_load_dword v2, v[2:3], off offset:-768

; #define PG8_STAGE(bufoff, gbase, voff) do { _Pragma("unroll") for (int _i = 0; _i < 2; ++_i) \
;         __builtin_amdgcn_global_load_lds((const unsigned*)((const char*)(gbase) + (voff)[_i]), (PG8_LAS unsigned*)(lds + (bufoff) + ldsw + _i * 8192), 16, 0, 0); } while (0)
; #define PG8_LDA(dst, b, h) do { _Pragma("unroll") for (int m = 0; m < 4; ++m) _Pragma("unroll") for (int k = 0; k < 2; ++k) dst[m][k] = *(const PG8_LAS bf16x8*)(lds + PG8_SA(b, h) + aoff + m * 2048 + k * 1024); } while (0)
; #define PG8_LDB(dst, b, h) do { _Pragma("unroll") for (int n = 0; n < 2; ++n) _Pragma("unroll") for (int k = 0; k < 2; ++k) dst[n][k] = *(const PG8_LAS bf16x8*)(lds + PG8_SB(b, h) + boff + n * 2048 + k * 1024); } while (0)
; #define PG8_WAIT_V(n) asm volatile("s_waitcnt vmcnt(" #n ")" ::: "memory")
; #define PG8_WAIT_L(n) asm volatile("s_waitcnt lgkmcnt(" #n ")" ::: "memory")
; #define PG8_BAR __builtin_amdgcn_s_barrier()
; #define PG8_SCHED __builtin_amdgcn_sched_barrier(0)
;     ...
;             const char* a1 = cA + (size_t)(t + 1) * kstep;
;             const char* a2 = last ? nA : cA + (size_t)(t + 2) * kstep; const char* b2 = last ? nB : cB + (size_t)(t + 2) * kstep;
;             const char* a3 = a2 + kstep; const char* b3 = b2 + kstep;
;             PG8_LDB(B0, 0, 0); PG8_LDB(B1, 0, 1); PG8_SCHED; PG8_LDA(At, 0, 0); PG8_STAGE(PG8_SA(1, 1), a1 + hstep, voffA);
;             PG8_WAIT_V(8); PG8_WAIT_L(0); PG8_BAR; PG8_MMA(0, 0, At, B0); PG8_MMA(0, 1, At, B1); PG8_BAR; PG8_SCHED;
.LBB0_206:
	s_add_u32 s72, s38, 0xfffc0080
	s_addc_u32 s73, s39, -1
	s_add_i32 s82, 0, 0x10000
	s_cmp_eq_u32 s81, 12
	s_cselect_b32 s77, s2, s73
	s_cselect_b32 s76, s31, s72
	s_cselect_b32 s73, s29, s80
	s_cselect_b32 s72, s60, s61
	s_add_i32 s86, 0, 0x14000
	s_waitcnt lgkmcnt(0)
	v_add_u32_e32 v156, s82, v195
	v_add_u32_e32 v183, s86, v195
	ds_read_b128 v[144:147], v156
	ds_read_b128 v[148:151], v156 offset:1024
	ds_read_b128 v[152:155], v156 offset:2048
	ds_read_b128 v[156:159], v156 offset:3072
	ds_read_b128 v[186:189], v183
	ds_read_b128 v[198:201], v183 offset:1024
	ds_read_b128 v[202:205], v183 offset:2048
	ds_read_b128 v[206:209], v183 offset:3072
	v_lshl_add_u64 v[242:243], s[38:39], 0, v[178:179]
	s_add_i32 m0, s63, 0xc000
	ds_read_b128 v[210:213], v197
	ds_read_b128 v[214:217], v197 offset:1024
	ds_read_b128 v[218:221], v197 offset:2048
	ds_read_b128 v[222:225], v197 offset:3072
	ds_read_b128 v[226:229], v197 offset:4096
	ds_read_b128 v[230:233], v197 offset:5120
	ds_read_b128 v[234:237], v197 offset:6144
	ds_read_b128 v[238:241], v197 offset:7168
	global_load_lds_dwordx4 v[242:243], off
	v_lshl_add_u64 v[242:243], s[38:39], 0, v[180:181]
	s_add_i32 m0, s63, 0xe000
	s_nop 0
	global_load_lds_dwordx4 v[242:243], off
	s_cmp_eq_u32 s101, 0
	s_cbranch_scc1 .Lpka_w8a
	s_cmp_eq_u32 s101, 4
	s_cbranch_scc1 .Lpka_s0
	s_cmp_eq_u32 s101, 3
	s_cbranch_scc1 .Lpka_s1
	s_cmp_eq_u32 s101, 2
	s_cbranch_scc1 .Lpka_s2
	global_store_dwordx4 v[254:255], v[12:15], off offset:64
	s_branch .Lpka_w9a
.Lpka_s0:
	global_store_dwordx4 v[254:255], v[0:3], off
	s_branch .Lpka_w9a
.Lpka_s1:
	global_store_dwordx4 v[254:255], v[4:7], off offset:64
	v_add_co_u32_e32 v254, vcc, s88, v254
	s_nop 1
	v_addc_co_u32_e32 v255, vcc, 0, v255, vcc
	s_branch .Lpka_w9a
.Lpka_s2:
	global_store_dwordx4 v[254:255], v[8:11], off

; #define PG8_STAGE(bufoff, gbase, voff) do { _Pragma("unroll") for (int _i = 0; _i < 2; ++_i) \
;         __builtin_amdgcn_global_load_lds((const unsigned*)((const char*)(gbase) + (voff)[_i]), (PG8_LAS unsigned*)(lds + (bufoff) + ldsw + _i * 8192), 16, 0, 0); } while (0)
; #define PG8_LDA(dst, b, h) do { _Pragma("unroll") for (int m = 0; m < 4; ++m) _Pragma("unroll") for (int k = 0; k < 2; ++k) dst[m][k] = *(const PG8_LAS bf16x8*)(lds + PG8_SA(b, h) + aoff + m * 2048 + k * 1024); } while (0)
; #define PG8_WAIT_V(n) asm volatile("s_waitcnt vmcnt(" #n ")" ::: "memory")
; #define PG8_WAIT_L(n) asm volatile("s_waitcnt lgkmcnt(" #n ")" ::: "memory")
; #define PG8_BAR __builtin_amdgcn_s_barrier()
; #define PG8_SCHED __builtin_amdgcn_sched_barrier(0)
;     ...
;             PG8_WAIT_V(8); PG8_WAIT_L(0); PG8_BAR; PG8_MMA(0, 0, At, B0); PG8_MMA(0, 1, At, B1); PG8_BAR; PG8_SCHED;
;             PG8_LDA(At, 0, 1); PG8_STAGE(PG8_SB(0, 0), b2, voffB); PG8_STAGE(PG8_SB(0, 1), b2 + hstepB, voffB); PG8_STAGE(PG8_SA(0, 0), a2, voffA);
.Lpka_da:
	s_waitcnt lgkmcnt(0)
	s_barrier
	s_setprio 1
	s_waitcnt lgkmcnt(0)
	v_mfma_f32_16x16x32_bf16 v[132:135], v[144:147], v[210:213], v[132:135]
	v_mfma_f32_16x16x32_bf16 v[128:131], v[152:155], v[210:213], v[128:131]
	v_mfma_f32_16x16x32_bf16 v[116:119], v[144:147], v[218:221], v[116:119]
	v_mfma_f32_16x16x32_bf16 v[112:115], v[152:155], v[218:221], v[112:115]
	v_mfma_f32_16x16x32_bf16 v[100:103], v[144:147], v[226:229], v[100:103]
	v_mfma_f32_16x16x32_bf16 v[96:99], v[152:155], v[226:229], v[96:99]
	v_mfma_f32_16x16x32_bf16 v[84:87], v[144:147], v[234:237], v[84:87]
	v_mfma_f32_16x16x32_bf16 v[80:83], v[152:155], v[234:237], v[80:83]
	v_mfma_f32_16x16x32_bf16 v[132:135], v[148:151], v[214:217], v[132:135]
	v_mfma_f32_16x16x32_bf16 v[128:131], v[156:159], v[214:217], v[128:131]
	v_mfma_f32_16x16x32_bf16 v[116:119], v[148:151], v[222:225], v[116:119]
	v_mfma_f32_16x16x32_bf16 v[112:115], v[156:159], v[222:225], v[112:115]
	v_mfma_f32_16x16x32_bf16 v[100:103], v[148:151], v[230:233], v[100:103]
	v_mfma_f32_16x16x32_bf16 v[96:99], v[156:159], v[230:233], v[96:99]
	v_mfma_f32_16x16x32_bf16 v[84:87], v[148:151], v[238:241], v[84:87]
	v_mfma_f32_16x16x32_bf16 v[80:83], v[156:159], v[238:241], v[80:83]
	s_setprio 0
	s_setprio 1
	v_mfma_f32_16x16x32_bf16 v[140:143], v[186:189], v[210:213], v[140:143]
	v_mfma_f32_16x16x32_bf16 v[136:139], v[202:205], v[210:213], v[136:139]
	v_mfma_f32_16x16x32_bf16 v[124:127], v[186:189], v[218:221], v[124:127]
	v_mfma_f32_16x16x32_bf16 v[120:123], v[202:205], v[218:221], v[120:123]
	v_mfma_f32_16x16x32_bf16 v[108:111], v[186:189], v[226:229], v[108:111]
	v_mfma_f32_16x16x32_bf16 v[104:107], v[202:205], v[226:229], v[104:107]
	v_mfma_f32_16x16x32_bf16 v[92:95], v[186:189], v[234:237], v[92:95]
	v_mfma_f32_16x16x32_bf16 v[88:91], v[202:205], v[234:237], v[88:91]
	v_mfma_f32_16x16x32_bf16 v[140:143], v[198:201], v[214:217], v[140:143]
	v_mfma_f32_16x16x32_bf16 v[136:139], v[206:209], v[214:217], v[136:139]
	v_mfma_f32_16x16x32_bf16 v[124:127], v[198:201], v[222:225], v[124:127]
	v_mfma_f32_16x16x32_bf16 v[120:123], v[206:209], v[222:225], v[120:123]
	v_mfma_f32_16x16x32_bf16 v[108:111], v[198:201], v[230:233], v[108:111]
	v_mfma_f32_16x16x32_bf16 v[104:107], v[206:209], v[230:233], v[104:107]
	v_mfma_f32_16x16x32_bf16 v[92:95], v[198:201], v[238:241], v[92:95]
	v_mfma_f32_16x16x32_bf16 v[88:91], v[206:209], v[238:241], v[88:91]
	s_setprio 0
	s_barrier
	s_add_i32 s82, s82, s15
	v_lshl_add_u64 v[242:243], s[72:73], 0, v[170:171]
	s_mov_b32 m0, s82
	ds_read_b128 v[210:213], v197 offset:16384
	ds_read_b128 v[214:217], v197 offset:17408
	ds_read_b128 v[218:221], v197 offset:18432
	ds_read_b128 v[222:225], v197 offset:19456
	ds_read_b128 v[226:229], v197 offset:20480
	ds_read_b128 v[230:233], v197 offset:21504
	ds_read_b128 v[234:237], v197 offset:22528
	ds_read_b128 v[238:241], v197 offset:23552
	global_load_lds_dwordx4 v[242:243], off
	s_add_i32 m0, s82, 0x2000
	s_add_u32 s82, s72, 0x10000
	v_lshl_add_u64 v[244:245], s[72:73], 0, v[166:167]
	s_addc_u32 s83, s73, 0
	s_add_i32 s86, s86, s15
	global_load_lds_dwordx4 v[244:245], off
	v_lshl_add_u64 v[246:247], s[82:83], 0, v[170:171]
	s_mov_b32 m0, s86
	v_lshl_add_u64 v[248:249], s[76:77], 0, v[168:169]
	global_load_lds_dwordx4 v[246:247], off
	v_lshl_add_u64 v[246:247], s[82:83], 0, v[166:167]
	s_add_i32 m0, s86, 0x2000
	s_nop 0
	global_load_lds_dwordx4 v[246:247], off
	v_lshl_add_u64 v[246:247], s[76:77], 0, v[172:173]
	s_mov_b32 m0, s63
	s_nop 0
	global_load_lds_dwordx4 v[246:247], off
	s_mov_b32 m0, s64
	s_nop 0
	global_load_lds_dwordx4 v[248:249], off
	s_cmp_eq_u32 s101, 0
	s_cbranch_scc1 .Lpka_w8b
	s_waitcnt vmcnt(9)
	s_branch .Lpka_db

; #define PG8_STAGE(bufoff, gbase, voff) do { _Pragma("unroll") for (int _i = 0; _i < 2; ++_i) \
;         __builtin_amdgcn_global_load_lds((const unsigned*)((const char*)(gbase) + (voff)[_i]), (PG8_LAS unsigned*)(lds + (bufoff) + ldsw + _i * 8192), 16, 0, 0); } while (0)
; #define PG8_LDA(dst, b, h) do { _Pragma("unroll") for (int m = 0; m < 4; ++m) _Pragma("unroll") for (int k = 0; k < 2; ++k) dst[m][k] = *(const PG8_LAS bf16x8*)(lds + PG8_SA(b, h) + aoff + m * 2048 + k * 1024); } while (0)
; #define PG8_LDB(dst, b, h) do { _Pragma("unroll") for (int n = 0; n < 2; ++n) _Pragma("unroll") for (int k = 0; k < 2; ++k) dst[n][k] = *(const PG8_LAS bf16x8*)(lds + PG8_SB(b, h) + boff + n * 2048 + k * 1024); } while (0)
; #define PG8_WAIT_V(n) asm volatile("s_waitcnt vmcnt(" #n ")" ::: "memory")
; #define PG8_WAIT_L(n) asm volatile("s_waitcnt lgkmcnt(" #n ")" ::: "memory")
; #define PG8_BAR __builtin_amdgcn_s_barrier()
; #define PG8_SCHED __builtin_amdgcn_sched_barrier(0)
;     ...
;             PG8_WAIT_V(8); PG8_WAIT_L(0); PG8_BAR; PG8_MMA(1, 0, At, B0); PG8_MMA(1, 1, At, B1); PG8_BAR; PG8_SCHED;
;             PG8_LDB(B0, 1, 0); PG8_LDB(B1, 1, 1); PG8_SCHED; PG8_LDA(At, 1, 0); PG8_STAGE(PG8_SA(0, 1), a2 + hstep, voffA);
.Lpka_db:
	s_waitcnt lgkmcnt(0)
	s_barrier
	s_setprio 1
	s_waitcnt lgkmcnt(0)
	v_mfma_f32_16x16x32_bf16 v[68:71], v[144:147], v[210:213], v[68:71]
	v_mfma_f32_16x16x32_bf16 v[64:67], v[152:155], v[210:213], v[64:67]
	v_mfma_f32_16x16x32_bf16 v[52:55], v[144:147], v[218:221], v[52:55]
	v_mfma_f32_16x16x32_bf16 v[48:51], v[152:155], v[218:221], v[48:51]
	v_mfma_f32_16x16x32_bf16 v[36:39], v[144:147], v[226:229], v[36:39]
	v_mfma_f32_16x16x32_bf16 v[32:35], v[152:155], v[226:229], v[32:35]
	v_mfma_f32_16x16x32_bf16 v[20:23], v[144:147], v[234:237], v[20:23]
	v_mfma_f32_16x16x32_bf16 v[16:19], v[152:155], v[234:237], v[16:19]
	v_mfma_f32_16x16x32_bf16 v[68:71], v[148:151], v[214:217], v[68:71]
	v_mfma_f32_16x16x32_bf16 v[64:67], v[156:159], v[214:217], v[64:67]
	v_mfma_f32_16x16x32_bf16 v[52:55], v[148:151], v[222:225], v[52:55]
	v_mfma_f32_16x16x32_bf16 v[48:51], v[156:159], v[222:225], v[48:51]
	v_mfma_f32_16x16x32_bf16 v[36:39], v[148:151], v[230:233], v[36:39]
	v_mfma_f32_16x16x32_bf16 v[32:35], v[156:159], v[230:233], v[32:35]
	v_mfma_f32_16x16x32_bf16 v[20:23], v[148:151], v[238:241], v[20:23]
	v_mfma_f32_16x16x32_bf16 v[16:19], v[156:159], v[238:241], v[16:19]
	s_setprio 0
	s_setprio 1
	v_mfma_f32_16x16x32_bf16 v[76:79], v[186:189], v[210:213], v[76:79]
	v_mfma_f32_16x16x32_bf16 v[72:75], v[202:205], v[210:213], v[72:75]
	v_mfma_f32_16x16x32_bf16 v[60:63], v[186:189], v[218:221], v[60:63]
	v_mfma_f32_16x16x32_bf16 v[56:59], v[202:205], v[218:221], v[56:59]
	v_mfma_f32_16x16x32_bf16 v[44:47], v[186:189], v[226:229], v[44:47]
	v_mfma_f32_16x16x32_bf16 v[40:43], v[202:205], v[226:229], v[40:43]
	v_mfma_f32_16x16x32_bf16 v[24:27], v[186:189], v[234:237], v[24:27]
	v_mfma_f32_16x16x32_bf16 v[28:31], v[202:205], v[234:237], v[28:31]
	v_mfma_f32_16x16x32_bf16 v[76:79], v[198:201], v[214:217], v[76:79]
	v_mfma_f32_16x16x32_bf16 v[72:75], v[206:209], v[214:217], v[72:75]
	v_mfma_f32_16x16x32_bf16 v[60:63], v[198:201], v[222:225], v[60:63]
	v_mfma_f32_16x16x32_bf16 v[56:59], v[206:209], v[222:225], v[56:59]
	v_mfma_f32_16x16x32_bf16 v[44:47], v[198:201], v[230:233], v[44:47]
	v_mfma_f32_16x16x32_bf16 v[40:43], v[206:209], v[230:233], v[40:43]
	v_mfma_f32_16x16x32_bf16 v[24:27], v[198:201], v[238:241], v[24:27]
	v_mfma_f32_16x16x32_bf16 v[28:31], v[206:209], v[238:241], v[28:31]
	s_setprio 0
	s_barrier
	s_add_i32 s82, 0, 0x18000
	s_add_i32 s83, 0, 0x1c000
	v_add_u32_e32 v156, s82, v195
	v_add_u32_e32 v183, s83, v195
	ds_read_b128 v[144:147], v156
	ds_read_b128 v[148:151], v156 offset:1024
	ds_read_b128 v[152:155], v156 offset:2048
	ds_read_b128 v[156:159], v156 offset:3072
	ds_read_b128 v[186:189], v183
	ds_read_b128 v[198:201], v183 offset:1024
	ds_read_b128 v[202:205], v183 offset:2048
	ds_read_b128 v[206:209], v183 offset:3072
	s_add_u32 s76, s76, 0x40000
	s_addc_u32 s77, s77, 0
	s_mov_b32 m0, s65
	v_lshl_add_u64 v[250:251], s[76:77], 0, v[172:173]
	ds_read_b128 v[210:213], v197 offset:32768
	ds_read_b128 v[214:217], v197 offset:33792
	ds_read_b128 v[218:221], v197 offset:34816
	ds_read_b128 v[222:225], v197 offset:35840
	ds_read_b128 v[226:229], v197 offset:36864
	ds_read_b128 v[230:233], v197 offset:37888
	ds_read_b128 v[234:237], v197 offset:38912
	ds_read_b128 v[238:241], v197 offset:39936
	global_load_lds_dwordx4 v[250:251], off
	v_lshl_add_u64 v[250:251], s[76:77], 0, v[168:169]
	s_mov_b32 m0, s66
	s_nop 0
	global_load_lds_dwordx4 v[250:251], off
	s_cmp_eq_u32 s101, 0
	s_cbranch_scc1 .Lpka_w8c
	s_waitcnt vmcnt(9)
	s_branch .Lpka_dc

; #define PG8_STAGE(bufoff, gbase, voff) do { _Pragma("unroll") for (int _i = 0; _i < 2; ++_i) \
;         __builtin_amdgcn_global_load_lds((const unsigned*)((const char*)(gbase) + (voff)[_i]), (PG8_LAS unsigned*)(lds + (bufoff) + ldsw + _i * 8192), 16, 0, 0); } while (0)
; #define PG8_LDA(dst, b, h) do { _Pragma("unroll") for (int m = 0; m < 4; ++m) _Pragma("unroll") for (int k = 0; k < 2; ++k) dst[m][k] = *(const PG8_LAS bf16x8*)(lds + PG8_SA(b, h) + aoff + m * 2048 + k * 1024); } while (0)
; #define PG8_WAIT_V(n) asm volatile("s_waitcnt vmcnt(" #n ")" ::: "memory")
; #define PG8_WAIT_L(n) asm volatile("s_waitcnt lgkmcnt(" #n ")" ::: "memory")
; #define PG8_BAR __builtin_amdgcn_s_barrier()
; #define PG8_SCHED __builtin_amdgcn_sched_barrier(0)
;     ...
;             PG8_WAIT_V(8); PG8_WAIT_L(0); PG8_BAR; PG8_MMA(0, 0, At, B0); PG8_MMA(0, 1, At, B1); PG8_BAR; PG8_SCHED;
;             PG8_LDA(At, 1, 1); PG8_STAGE(PG8_SB(1, 0), b3, voffB); PG8_STAGE(PG8_SB(1, 1), b3 + hstepB, voffB); PG8_STAGE(PG8_SA(1, 0), a3, voffA);
;             PG8_WAIT_V(8); PG8_WAIT_L(0); PG8_BAR; PG8_MMA(1, 0, At, B0); PG8_MMA(1, 1, At, B1); PG8_BAR; PG8_SCHED;
;         }
.Lpka_dc:
	s_waitcnt lgkmcnt(0)
	s_barrier
	s_setprio 1
	s_waitcnt lgkmcnt(0)
	v_mfma_f32_16x16x32_bf16 v[132:135], v[144:147], v[210:213], v[132:135]
	v_mfma_f32_16x16x32_bf16 v[128:131], v[152:155], v[210:213], v[128:131]
	v_mfma_f32_16x16x32_bf16 v[116:119], v[144:147], v[218:221], v[116:119]
	v_mfma_f32_16x16x32_bf16 v[112:115], v[152:155], v[218:221], v[112:115]
	v_mfma_f32_16x16x32_bf16 v[100:103], v[144:147], v[226:229], v[100:103]
	v_mfma_f32_16x16x32_bf16 v[96:99], v[152:155], v[226:229], v[96:99]
	v_mfma_f32_16x16x32_bf16 v[84:87], v[144:147], v[234:237], v[84:87]
	v_mfma_f32_16x16x32_bf16 v[80:83], v[152:155], v[234:237], v[80:83]
	v_mfma_f32_16x16x32_bf16 v[132:135], v[148:151], v[214:217], v[132:135]
	v_mfma_f32_16x16x32_bf16 v[128:131], v[156:159], v[214:217], v[128:131]
	v_mfma_f32_16x16x32_bf16 v[116:119], v[148:151], v[222:225], v[116:119]
	v_mfma_f32_16x16x32_bf16 v[112:115], v[156:159], v[222:225], v[112:115]
	v_mfma_f32_16x16x32_bf16 v[100:103], v[148:151], v[230:233], v[100:103]
	v_mfma_f32_16x16x32_bf16 v[96:99], v[156:159], v[230:233], v[96:99]
	v_mfma_f32_16x16x32_bf16 v[84:87], v[148:151], v[238:241], v[84:87]
	v_mfma_f32_16x16x32_bf16 v[80:83], v[156:159], v[238:241], v[80:83]
	s_setprio 0
	s_setprio 1
	v_mfma_f32_16x16x32_bf16 v[140:143], v[186:189], v[210:213], v[140:143]
	v_mfma_f32_16x16x32_bf16 v[136:139], v[202:205], v[210:213], v[136:139]
	v_mfma_f32_16x16x32_bf16 v[124:127], v[186:189], v[218:221], v[124:127]
	v_mfma_f32_16x16x32_bf16 v[120:123], v[202:205], v[218:221], v[120:123]
	v_mfma_f32_16x16x32_bf16 v[108:111], v[186:189], v[226:229], v[108:111]
	v_mfma_f32_16x16x32_bf16 v[104:107], v[202:205], v[226:229], v[104:107]
	v_mfma_f32_16x16x32_bf16 v[92:95], v[186:189], v[234:237], v[92:95]
	v_mfma_f32_16x16x32_bf16 v[88:91], v[202:205], v[234:237], v[88:91]
	v_mfma_f32_16x16x32_bf16 v[140:143], v[198:201], v[214:217], v[140:143]
	v_mfma_f32_16x16x32_bf16 v[136:139], v[206:209], v[214:217], v[136:139]
	v_mfma_f32_16x16x32_bf16 v[124:127], v[198:201], v[222:225], v[124:127]
	v_mfma_f32_16x16x32_bf16 v[120:123], v[206:209], v[222:225], v[120:123]
	v_mfma_f32_16x16x32_bf16 v[108:111], v[198:201], v[230:233], v[108:111]
	v_mfma_f32_16x16x32_bf16 v[104:107], v[206:209], v[230:233], v[104:107]
	v_mfma_f32_16x16x32_bf16 v[92:95], v[198:201], v[238:241], v[92:95]
	v_mfma_f32_16x16x32_bf16 v[88:91], v[206:209], v[238:241], v[88:91]
	s_setprio 0
	s_barrier
	s_add_i32 s76, s82, s15
	v_lshl_add_u64 v[242:243], v[242:243], 0, s[4:5]
	s_mov_b32 m0, s76
	ds_read_b128 v[210:213], v197 offset:49152
	ds_read_b128 v[214:217], v197 offset:50176
	ds_read_b128 v[218:221], v197 offset:51200
	ds_read_b128 v[222:225], v197 offset:52224
	ds_read_b128 v[226:229], v197 offset:53248
	ds_read_b128 v[230:233], v197 offset:54272
	ds_read_b128 v[234:237], v197 offset:55296
	ds_read_b128 v[238:241], v197 offset:56320
	global_load_lds_dwordx4 v[242:243], off
	s_add_i32 m0, s76, 0x2000
	s_add_u32 s72, s72, 0x10080
	v_lshl_add_u64 v[242:243], v[244:245], 0, s[4:5]
	s_addc_u32 s73, s73, 0
	s_add_i32 s76, s83, s15
	global_load_lds_dwordx4 v[242:243], off
	v_lshl_add_u64 v[242:243], s[72:73], 0, v[170:171]
	s_mov_b32 m0, s76
	s_nop 0
	global_load_lds_dwordx4 v[242:243], off
	v_lshl_add_u64 v[242:243], s[72:73], 0, v[166:167]
	s_add_i32 m0, s76, 0x2000
	s_nop 0
	global_load_lds_dwordx4 v[242:243], off
	v_lshl_add_u64 v[242:243], v[246:247], 0, s[4:5]
	s_mov_b32 m0, s74
	s_nop 0
	global_load_lds_dwordx4 v[242:243], off
	v_lshl_add_u64 v[242:243], v[248:249], 0, s[4:5]
	s_mov_b32 m0, s75
	s_nop 0
	global_load_lds_dwordx4 v[242:243], off
	s_waitcnt vmcnt(8)
	s_waitcnt lgkmcnt(0)
	s_barrier
	s_setprio 1
	s_waitcnt lgkmcnt(0)
	v_mfma_f32_16x16x32_bf16 v[68:71], v[144:147], v[210:213], v[68:71]
	v_mfma_f32_16x16x32_bf16 v[64:67], v[152:155], v[210:213], v[64:67]
	v_mfma_f32_16x16x32_bf16 v[52:55], v[144:147], v[218:221], v[52:55]
	v_mfma_f32_16x16x32_bf16 v[48:51], v[152:155], v[218:221], v[48:51]
	v_mfma_f32_16x16x32_bf16 v[36:39], v[144:147], v[226:229], v[36:39]
	v_mfma_f32_16x16x32_bf16 v[32:35], v[152:155], v[226:229], v[32:35]
	v_mfma_f32_16x16x32_bf16 v[20:23], v[144:147], v[234:237], v[20:23]
	v_mfma_f32_16x16x32_bf16 v[16:19], v[152:155], v[234:237], v[16:19]
	v_mfma_f32_16x16x32_bf16 v[68:71], v[148:151], v[214:217], v[68:71]
	v_mfma_f32_16x16x32_bf16 v[64:67], v[156:159], v[214:217], v[64:67]
	v_mfma_f32_16x16x32_bf16 v[52:55], v[148:151], v[222:225], v[52:55]
	v_mfma_f32_16x16x32_bf16 v[48:51], v[156:159], v[222:225], v[48:51]
	v_mfma_f32_16x16x32_bf16 v[36:39], v[148:151], v[230:233], v[36:39]
	v_mfma_f32_16x16x32_bf16 v[32:35], v[156:159], v[230:233], v[32:35]
	v_mfma_f32_16x16x32_bf16 v[20:23], v[148:151], v[238:241], v[20:23]
	v_mfma_f32_16x16x32_bf16 v[16:19], v[156:159], v[238:241], v[16:19]
	s_setprio 0
	s_setprio 1
	v_mfma_f32_16x16x32_bf16 v[76:79], v[186:189], v[210:213], v[76:79]
	v_mfma_f32_16x16x32_bf16 v[72:75], v[202:205], v[210:213], v[72:75]
	v_mfma_f32_16x16x32_bf16 v[60:63], v[186:189], v[218:221], v[60:63]
	v_mfma_f32_16x16x32_bf16 v[56:59], v[202:205], v[218:221], v[56:59]
	v_mfma_f32_16x16x32_bf16 v[44:47], v[186:189], v[226:229], v[44:47]
	v_mfma_f32_16x16x32_bf16 v[40:43], v[202:205], v[226:229], v[40:43]
	v_mfma_f32_16x16x32_bf16 v[24:27], v[186:189], v[234:237], v[24:27]
	v_mfma_f32_16x16x32_bf16 v[28:31], v[202:205], v[234:237], v[28:31]
	v_mfma_f32_16x16x32_bf16 v[76:79], v[198:201], v[214:217], v[76:79]
	v_mfma_f32_16x16x32_bf16 v[72:75], v[206:209], v[214:217], v[72:75]
	v_mfma_f32_16x16x32_bf16 v[60:63], v[198:201], v[222:225], v[60:63]
	v_mfma_f32_16x16x32_bf16 v[56:59], v[206:209], v[222:225], v[56:59]
	v_mfma_f32_16x16x32_bf16 v[44:47], v[198:201], v[230:233], v[44:47]
	v_mfma_f32_16x16x32_bf16 v[40:43], v[206:209], v[230:233], v[40:43]
	v_mfma_f32_16x16x32_bf16 v[24:27], v[198:201], v[238:241], v[24:27]
	v_mfma_f32_16x16x32_bf16 v[28:31], v[206:209], v[238:241], v[28:31]
	s_setprio 0
	s_barrier
	s_cmp_eq_u32 s101, 0
	s_cbranch_scc1 .Lpka_t
	s_sub_u32 s101, s101, 1
.Lpka_t:
	s_add_i32 s81, s81, 2
	s_add_u32 s38, s38, 0x100
	s_addc_u32 s39, s39, 0
	s_add_u32 s61, s61, 0x100
	s_addc_u32 s80, s80, 0
	s_cmp_gt_u32 s81, 13
	s_cbranch_scc0 .LBB0_206
	s_and_b64 vcc, exec, s[22:23]
	s_cbranch_vccz .LBB0_209
	s_barrier

;     __device__ __forceinline__ void side_issue(Side& s, int ui, int c, int wid, int lane) const {
;         s.row = (c * upc + ui) * 8 + wid;
;         if (MODE == 0 && s.row < xrows) { const f32x4* xr = (const f32x4*)(xs + (size_t)s.row * 1024) + lane;
; #pragma unroll
;             for (int j = 0; j < 4; ++j) s.v[j] = __builtin_nontemporal_load(xr + 64 * j); }
;     }
.LBB0_221:
	s_add_i32 s2, s27, s43
	s_lshl_b32 s2, s2, 3
	s_add_i32 s76, s2, s14
	s_cmp_lt_i32 s76, s95
	s_cselect_b64 s[80:81], -1, 0
	s_cmp_ge_i32 s76, s95
	s_cbranch_scc1 .LBB0_223
	s_ashr_i32 s77, s76, 31
	s_lshl_b64 s[38:39], s[76:77], 12
	v_lshl_add_u64 v[198:199], v[174:175], 0, s[38:39]
	global_load_dwordx4 v[210:213], v[198:199], off nt
	global_load_dwordx4 v[206:209], v[198:199], off offset:1024 nt
	global_load_dwordx4 v[202:205], v[198:199], off offset:2048 nt
	s_nop 0
	global_load_dwordx4 v[198:201], v[198:199], off offset:3072 nt

;     __device__ __forceinline__ void side_finish(const Side& s, int lane) const {
;         if (MODE == 0 && s.row < xrows) {
;             float q = 0.f;
; #pragma unroll
;             for (int j = 0; j < 4; ++j) q += (s.v[j][0] * s.v[j][0] + s.v[j][1] * s.v[j][1]) + (s.v[j][2] * s.v[j][2] + s.v[j][3] * s.v[j][3]);
;             const float rstd = __builtin_amdgcn_rsqf(wave_sum(q) * (1.0f / 1024.0f) + 1e-6f);
;             const bool odd = lane & 1;
;             bf16_t* orow = xd + (size_t)s.row * 1024 + 4 * (lane & ~1);
; #pragma unroll
;             for (int jp = 0; jp < 2; ++jp) {
;                 const int ja = 2 * jp, jb = 2 * jp + 1;
;                 const unsigned pax = cvt_pk_bf16(s.v[ja][0] * rstd, s.v[ja][1] * rstd), pay = cvt_pk_bf16(s.v[ja][2] * rstd, s.v[ja][3] * rstd);
;                 const unsigned pbx = cvt_pk_bf16(s.v[jb][0] * rstd, s.v[jb][1] * rstd), pby = cvt_pk_bf16(s.v[jb][2] * rstd, s.v[jb][3] * rstd);
;                 const unsigned rx = (unsigned)__builtin_amdgcn_update_dpp(0, (int)(odd ? pax : pbx), 0xB1, 0xF, 0xF, true), ry = (unsigned)__builtin_amdgcn_update_dpp(0, (int)(odd ? pay : pby), 0xB1, 0xF, 0xF, true);
;     __device__ __forceinline__ void operator()(const f32x4 (&acc)[2][2][4][2], const Unit& u, int wr, int wc, int fr, int fq, const bool reuse, PG8_LAS float* rscr, PG8_LAS const float* gains) const {
;     ...
;                 if (type < 2) {
;                     float ss = 0.f;
; #pragma unroll
;                     for (int bj = 0; bj < 2; ++bj)
; #pragma unroll
;                         for (int n = 0; n < 2; ++n) { const f32x4 x = v[bj][n]; ss += (x[0] * x[0] + x[1] * x[1]) + (x[2] * x[2] + x[3] * x[3]); }
;                     ss = sum_x16(ss); ss = sum_x32(ss);
;                     const float inv = __builtin_amdgcn_rsqf(ss * (1.0f / 64.0f) + RMS_EPS);
; #pragma unroll
;                     for (int bj = 0; bj < 2; ++bj)
; #pragma unroll
;                         for (int n = 0; n < 2; ++n) v[bj][n] = v[bj][n] * gv[bj][n] * inv;
;                 }
;                 bf16_t* p = p0 + (size_t)(8 * ai + m) * step16;
; #pragma unroll
;                 for (int bj = 0; bj < 2; ++bj) { u32x4 w; w.x = cvt_pk_bf16(v[bj][0][0], v[bj][0][1]); w.y = cvt_pk_bf16(v[bj][0][2], v[bj][0][3]); w.z = cvt_pk_bf16(v[bj][1][0], v[bj][1][1]); w.w = cvt_pk_bf16(v[bj][1][2], v[bj][1][3]);
;                     st16_wt(p + 32 * bj, w); }
.LBB0_244:
	s_nop 0
	v_lshl_add_u64 v[48:49], v[64:65], 0, s[88:89]
	v_mov_b32_e32 v254, v48
	v_mov_b32_e32 v255, v49
	s_and_b64 vcc, exec, s[38:39]
	v_cvt_pk_bf16_f32 v36, v36, v37
	v_cvt_pk_bf16_f32 v37, v38, v39
	v_cvt_pk_bf16_f32 v38, v32, v33
	v_cvt_pk_bf16_f32 v39, v34, v35
	v_mov_b32_e32 v0, v36
	v_mov_b32_e32 v1, v37
	v_mov_b32_e32 v2, v38
	v_mov_b32_e32 v3, v39
	v_cvt_pk_bf16_f32 v32, v44, v45
	v_cvt_pk_bf16_f32 v33, v46, v47
	v_cvt_pk_bf16_f32 v34, v40, v41
	v_cvt_pk_bf16_f32 v35, v42, v43
	v_mov_b32_e32 v4, v32
	v_mov_b32_e32 v5, v33
	v_mov_b32_e32 v6, v34
	v_mov_b32_e32 v7, v35
	s_cbranch_vccnz .LBB0_246
	s_nop 0
	v_mul_f32_e32 v32, v21, v21
	v_mul_f32_e32 v33, v23, v23
	v_fmac_f32_e32 v32, v20, v20
	v_fmac_f32_e32 v33, v22, v22
	v_add_f32_e32 v32, v32, v33
	v_mul_f32_e32 v33, v17, v17
	v_mul_f32_e32 v34, v19, v19
	v_fmac_f32_e32 v33, v16, v16
	v_fmac_f32_e32 v34, v18, v18
	v_add_f32_e32 v33, v33, v34
	v_add_f32_e32 v32, v32, v33
	v_mul_f32_e32 v33, v25, v25
	v_mul_f32_e32 v34, v27, v27
	v_fmac_f32_e32 v33, v24, v24
	v_fmac_f32_e32 v34, v26, v26
	v_add_f32_e32 v33, v33, v34
	v_add_f32_e32 v32, v32, v33
	v_mul_f32_e32 v33, v29, v29
	v_mul_f32_e32 v34, v31, v31
	v_fmac_f32_e32 v33, v28, v28
	v_fmac_f32_e32 v34, v30, v30
	v_add_f32_e32 v33, v33, v34
	v_add_f32_e32 v32, v32, v33
	v_mov_b32_e32 v33, v32
	s_nop 1
	v_permlane16_swap_b32_e32 v32, v33
	v_add_f32_e32 v32, v32, v33
	v_mov_b32_e32 v33, v32
	s_nop 1
	v_permlane32_swap_b32_e32 v32, v33
	v_add_f32_e32 v32, v32, v33
	v_fmamk_f32 v32, v32, 0x3c800000, v190
	v_rsq_f32_e32 v32, v32
	s_waitcnt lgkmcnt(0)
	v_pk_mul_f32 v[22:23], v[22:23], v[158:159]
	v_pk_mul_f32 v[20:21], v[20:21], v[156:157]
	v_pk_mul_f32 v[18:19], v[18:19], v[154:155]
	v_pk_mul_f32 v[16:17], v[16:17], v[152:153]
	v_pk_mul_f32 v[26:27], v[26:27], v[150:151]
	v_pk_mul_f32 v[24:25], v[24:25], v[148:149]
	v_pk_mul_f32 v[30:31], v[30:31], v[146:147]
	v_pk_mul_f32 v[28:29], v[28:29], v[144:145]
	v_pk_mul_f32 v[22:23], v[22:23], v[32:33] op_sel_hi:[1,0]
	v_pk_mul_f32 v[20:21], v[20:21], v[32:33] op_sel_hi:[1,0]
	v_pk_mul_f32 v[18:19], v[18:19], v[32:33] op_sel_hi:[1,0]
	v_pk_mul_f32 v[16:17], v[16:17], v[32:33] op_sel_hi:[1,0]
	v_pk_mul_f32 v[26:27], v[26:27], v[32:33] op_sel_hi:[1,0]
	v_pk_mul_f32 v[24:25], v[24:25], v[32:33] op_sel_hi:[1,0]
	v_pk_mul_f32 v[30:31], v[30:31], v[32:33] op_sel_hi:[1,0]
	v_pk_mul_f32 v[28:29], v[28:29], v[32:33] op_sel_hi:[1,0]
.LBB0_246:
	s_nop 0
	v_lshl_add_u64 v[32:33], v[48:49], 0, s[88:89]
	s_andn2_b64 vcc, exec, s[80:81]
	v_cvt_pk_bf16_f32 v20, v20, v21
	v_cvt_pk_bf16_f32 v21, v22, v23
	v_cvt_pk_bf16_f32 v22, v16, v17
	v_cvt_pk_bf16_f32 v23, v18, v19
	v_mov_b32_e32 v8, v20
	v_mov_b32_e32 v9, v21
	v_mov_b32_e32 v10, v22
	v_mov_b32_e32 v11, v23
	v_cvt_pk_bf16_f32 v16, v24, v25
	v_cvt_pk_bf16_f32 v17, v26, v27
	v_cvt_pk_bf16_f32 v18, v28, v29
	v_cvt_pk_bf16_f32 v19, v30, v31
	v_mov_b32_e32 v12, v16
	v_mov_b32_e32 v13, v17
	v_mov_b32_e32 v14, v18
	v_mov_b32_e32 v15, v19
	s_mov_b32 s101, 4
	s_cbranch_vccnz .LBB0_248
	s_waitcnt vmcnt(12)
	v_mul_f32_e32 v16, v211, v211
	v_mul_f32_e32 v17, v213, v213
	v_fmac_f32_e32 v16, v210, v210
	v_fmac_f32_e32 v17, v212, v212
	v_add_f32_e32 v16, v16, v17
	v_mul_f32_e32 v17, v207, v207
	v_mul_f32_e32 v18, v209, v209
	v_fmac_f32_e32 v17, v206, v206
	v_fmac_f32_e32 v18, v208, v208
	v_add_f32_e32 v17, v17, v18
	v_add_f32_e32 v16, v17, v16
	v_mul_f32_e32 v17, v203, v203
	v_mul_f32_e32 v18, v205, v205
	v_fmac_f32_e32 v17, v202, v202
	v_fmac_f32_e32 v18, v204, v204
	v_add_f32_e32 v17, v17, v18
	v_add_f32_e32 v16, v17, v16
	v_mul_f32_e32 v17, v199, v199
	v_mul_f32_e32 v18, v201, v201
	v_fmac_f32_e32 v17, v198, v198
	v_fmac_f32_e32 v18, v200, v200
	v_add_f32_e32 v17, v17, v18
	v_add_f32_e32 v16, v17, v16
	s_ashr_i32 s77, s76, 31
	s_lshl_b64 s[12:13], s[76:77], 11
	v_add_f32_dpp v16, v16, v16 quad_perm:[1,0,3,2] row_mask:0xf bank_mask:0xf bound_ctrl:1
	v_lshl_add_u64 v[20:21], v[176:177], 0, s[12:13]
	v_mov_b32_e32 v183, v161
	v_add_f32_dpp v16, v16, v16 quad_perm:[2,3,0,1] row_mask:0xf bank_mask:0xf bound_ctrl:1
	v_mov_b32_e32 v185, v161
	s_nop 0
	v_add_f32_dpp v16, v16, v16 row_half_mirror row_mask:0xf bank_mask:0xf bound_ctrl:1
	s_nop 1
	v_add_f32_dpp v16, v16, v16 row_mirror row_mask:0xf bank_mask:0xf bound_ctrl:1
	v_mov_b32_e32 v17, v16
	s_nop 1
	v_permlane16_swap_b32_e32 v16, v17
	v_add_f32_e32 v16, v16, v17
	v_mov_b32_e32 v17, v16
	s_nop 1
	v_permlane32_swap_b32_e32 v16, v17
	v_add_f32_e32 v16, v16, v17
	v_fmamk_f32 v16, v16, 0x3a800000, v190
	v_rsq_f32_e32 v24, v16
	s_nop 0
	v_mul_f32_e32 v16, v210, v24
	v_mul_f32_e32 v17, v211, v24
	v_cvt_pk_bf16_f32 v16, v16, v17
	v_mul_f32_e32 v17, v212, v24
	v_mul_f32_e32 v18, v213, v24
	v_cvt_pk_bf16_f32 v17, v17, v18
	v_mul_f32_e32 v18, v206, v24
	v_mul_f32_e32 v19, v207, v24
	v_cvt_pk_bf16_f32 v18, v18, v19
	v_mul_f32_e32 v19, v208, v24
	v_mul_f32_e32 v22, v209, v24
	v_cvt_pk_bf16_f32 v19, v19, v22
	v_cndmask_b32_e64 v22, v16, v18, s[34:35]
	v_cndmask_b32_e64 v23, v17, v19, s[34:35]
	s_nop 0
	v_mov_b32_dpp v22, v22 quad_perm:[1,0,3,2] row_mask:0xf bank_mask:0xf bound_ctrl:1
	v_mov_b32_dpp v23, v23 quad_perm:[1,0,3,2] row_mask:0xf bank_mask:0xf bound_ctrl:1
	v_cndmask_b32_e64 v16, v22, v16, s[34:35]
	v_cndmask_b32_e64 v17, v23, v17, s[34:35]
	v_cndmask_b32_e64 v18, v18, v22, s[34:35]
	v_cndmask_b32_e64 v19, v19, v23, s[34:35]
	v_lshl_add_u64 v[22:23], v[20:21], 0, v[182:183]
	global_store_dwordx4 v[22:23], v[16:19], off
	v_mul_f32_e32 v22, v201, v24
	v_lshl_add_u64 v[20:21], v[20:21], 0, v[184:185]
	v_mul_f32_e32 v16, v202, v24
	v_mul_f32_e32 v17, v203, v24
	v_cvt_pk_bf16_f32 v16, v16, v17
	v_mul_f32_e32 v17, v204, v24
	v_mul_f32_e32 v18, v205, v24
	v_cvt_pk_bf16_f32 v17, v17, v18
	v_mul_f32_e32 v18, v198, v24
	v_mul_f32_e32 v19, v199, v24
	v_cvt_pk_bf16_f32 v18, v18, v19
	v_mul_f32_e32 v19, v200, v24
	v_cvt_pk_bf16_f32 v19, v19, v22
	v_cndmask_b32_e64 v22, v16, v18, s[34:35]
	v_cndmask_b32_e64 v23, v17, v19, s[34:35]
	s_nop 0
	v_mov_b32_dpp v22, v22 quad_perm:[1,0,3,2] row_mask:0xf bank_mask:0xf bound_ctrl:1
	v_mov_b32_dpp v23, v23 quad_perm:[1,0,3,2] row_mask:0xf bank_mask:0xf bound_ctrl:1
	v_cndmask_b32_e64 v16, v22, v16, s[34:35]
	v_cndmask_b32_e64 v17, v23, v17, s[34:35]
	v_cndmask_b32_e64 v18, v18, v22, s[34:35]
	v_cndmask_b32_e64 v19, v19, v23, s[34:35]
	global_store_dwordx4 v[20:21], v[16:19], off

; #define PG8_ZERO4(x) do { unsigned long long z0_, z1_; asm volatile("v_mov_b64 %0, 0\n\tv_mov_b64 %1, 0" : "=v"(z0_), "=v"(z1_)); typedef unsigned long long u64x2_ __attribute__((ext_vector_type(2))); (x) = __builtin_bit_cast(f32x4, (u64x2_){z0_, z1_}); } while (0)
; #define PG8_WAIT_V(n) asm volatile("s_waitcnt vmcnt(" #n ")" ::: "memory")
; #define PG8_BAR __builtin_amdgcn_s_barrier()
;     ...
;         if (!has_next) break;
; #pragma unroll
;         for (int a = 0; a < 2; ++a)
; #pragma unroll
;             for (int b = 0; b < 2; ++b)
; #pragma unroll
;                 for (int m = 0; m < 4; ++m)
; #pragma unroll
;                     for (int n = 0; n < 2; ++n) PG8_ZERO4(acc[a][b][m][n]);
;         cur = nxt; cA = nA; cB = nB; ++ui;
;         if constexpr (ALIGN_EPI) { if (wr == 1) PG8_BAR; }
;     }
;     PG8_WAIT_V(0);
;     if constexpr (!ALIGN_EPI) { if (wr == 0) PG8_BAR; }
;     PG8_BAR;
.LBB0_253:
	s_cmp_eq_u32 s101, 0
	s_cbranch_scc1 .Lpka_fd
	global_store_dwordx4 v[254:255], v[0:3], off
	global_store_dwordx4 v[254:255], v[4:7], off offset:64
	v_add_co_u32_e32 v254, vcc, s88, v254
	s_nop 1
	v_addc_co_u32_e32 v255, vcc, 0, v255, vcc
	global_store_dwordx4 v[254:255], v[8:11], off
	global_store_dwordx4 v[254:255], v[12:15], off offset:64
	s_mov_b32 s101, 0
